# GLA scan prologue: step-0 q/k and low-rank loads issued before the compiled prologue's single vmcnt(0) wait (one memory round trip instead of two); obsolete offset block dropped
# speedup vs baseline: 1.0097x; 1.0097x over previous
; __device__ __forceinline__ void scan_unit(const int unit, const Args& a, unsigned char* lds, const int mk_wid) {
;     ...
;     GLA_LOAD(0);
.LBB0_416:
	s_or_b64 exec, exec, s[22:23]
	s_mov_b32 s4, 0x2a00000
	s_and_b64 s[20:21], s[2:3], exec
	s_cselect_b32 s4, s4, 0x1aa00000
	s_add_u32 s4, s38, s4
	s_addc_u32 s9, s39, 0
	s_lshl_b64 s[20:21], s[18:19], 11
	s_lshl_b32 s18, s35, 1
	s_add_u32 s18, s4, s18
	s_addc_u32 s19, s9, 0
	s_lshr_b32 s4, s33, 8
	s_lshl_b32 s9, s4, 10
	s_add_i32 s44, s9, 0
	s_lshl_b32 s4, s4, 14
	s_add_i32 s9, 0, 0x16c00
	s_add_i32 s45, s9, s4
	s_lshl_b32 s22, s34, 2
	s_add_i32 s44, s44, 0x1ec00
	s_add_i32 s45, s45, s22
	s_lshl_b32 s22, s27, 1
	s_add_u32 s22, s38, s22
	s_addc_u32 s23, s39, 0
	s_add_u32 s22, s22, 0xd600000
	s_addc_u32 s23, s23, 0
	s_cmpk_lt_u32 s33, 0x100
	v_lshl_add_u64 v[152:153], v[0:1], 1, s[24:25]
	s_cselect_b64 s[24:25], -1, 0
	s_lshl_b32 s27, s70, 4
	s_and_b32 s46, s27, 0x3fffffe0
	s_lshl_b32 s27, s70, 5
	s_and_b32 s47, s27, 32
	s_cmp_lg_u32 0, -1
	s_cselect_b32 s27, 0, 0
	s_add_i32 s4, s27, s4
	s_lshl_b32 s26, s26, 9
	s_add_i32 s48, s4, s26
	v_mov_b32_e32 v155, 0
	v_mbcnt_lo_u32_b32 v66, -1, 0
	v_mbcnt_hi_u32_b32 v66, -1, v66
	s_lshl_b32 s96, s70, 3
	s_sub_i32 s97, 56, s96
	s_bitcmp1_b32 s8, 0
	s_cselect_b32 s96, s97, s96
	s_add_i32 s96, s96, s12
	s_lshl_b32 s96, s96, 10
	v_lshl_add_u32 v245, v66, 2, s96
	s_bitcmp1_b32 s8, 0
	s_cselect_b32 s97, 3, 0
	s_lshl_b32 s97, s97, 16
	v_add_u32_e32 v64, s97, v245
	v_add_u32_e32 v65, 0x1000, v64
	s_bitcmp1_b32 s8, 0
	s_cbranch_scc1 .Lscan_qk_rev2
	global_load_dword v100, v64, s[14:15]
	global_load_dword v101, v64, s[14:15] offset:1024
	global_load_dword v102, v64, s[14:15] offset:2048
	global_load_dword v103, v64, s[14:15] offset:3072
	global_load_dword v104, v65, s[14:15]
	global_load_dword v105, v65, s[14:15] offset:1024
	global_load_dword v106, v65, s[14:15] offset:2048
	global_load_dword v107, v65, s[14:15] offset:3072
	s_branch .Lscan_qk_done2

; __device__ __forceinline__ unsigned pk2(float lo, float hi) { f32x2_t v = {lo, hi}; bf16x2_t b = __builtin_convertvector(v, bf16x2_t); return __builtin_bit_cast(unsigned, b); }
; __device__ __forceinline__ void scan_unit(const int unit, const Args& a, unsigned char* lds, const int mk_wid) {
;     ...
;     { const int l_ = MK_TID & 63, r32 = l_ & 31, hi = l_ >> 5; const float* up = a.in[dir ? 12 : 10] + (size_t)(8 * hi) * 512 + h * 128 + (wid & 3) * 32 + r32;
;       v4u w; w.x = pk2(up[0], up[512]); w.y = pk2(up[2 * 512], up[3 * 512]); w.z = pk2(up[4 * 512], up[5 * 512]); w.w = pk2(up[6 * 512], up[7 * 512]);
;       upf = __builtin_bit_cast(bf16x8, w); biasc = a.in[dir ? 13 : 11][h * 128 + (wid & 3) * 32 + r32]; }
;     u16* qe = (u16*)(lds + L_QE); u16* ke = (u16*)(lds + L_KE); u16* am = (u16*)(lds + L_AM);
;     float* las = (float*)(lds + L_LAS); float* gs = (float*)(lds + L_GS); float* dl = (float*)(lds + L_DL);
;     const int ldsb = (int)(uintptr_t)lds;
;     u16* ot = (u16*)(lds + L_LAS);
;     int pend_cc = -1;
;     ...
;     f32x16 S[4]; S[0] = f32x16{}; S[1] = f32x16{}; S[2] = f32x16{}; S[3] = f32x16{};
;     bf16x8 qraw[2], kraw[2], vraw[4]; bf16x8 lraw = bf16x8{};
;     ...
;     GLA_LOAD(0);
.Lscan_qk_done2:
	v_mov_b32_e32 v128, 0
	v_mov_b32_e32 v129, 0
	v_mov_b32_e32 v130, 0
	v_mov_b32_e32 v131, 0
	v_mov_b32_e32 v132, 0
	v_mov_b32_e32 v133, 0
	v_mov_b32_e32 v134, 0
	v_mov_b32_e32 v135, 0
	v_mbcnt_lo_u32_b32 v66, -1, 0
	v_mbcnt_hi_u32_b32 v66, -1, v66
	s_lshr_b32 s96, s70, 2
	s_lshl_b32 s96, s96, 5
	v_and_b32_e32 v67, 31, v66
	v_add_u32_e32 v67, s96, v67
	v_sub_u32_e32 v68, 63, v67
	v_cndmask_b32_e64 v67, v68, v67, s[2:3]
	v_add_u32_e32 v67, s12, v67
	v_bfe_u32 v68, v66, 5, 1
	v_lshlrev_b32_e32 v68, 4, v68
	v_lshl_add_u32 v251, v67, 6, v68
	s_bitcmp1_b32 s8, 0
	s_cselect_b32 s97, 3, 0
	s_lshl_b32 s97, s97, 12
	v_add_u32_e32 v70, s97, v251
	v_mov_b32_e32 v71, 0
	v_lshl_add_u64 v[70:71], v[152:153], 0, v[70:71]
	global_load_dwordx4 v[96:99], v[70:71], off
	v_lshrrev_b32_e32 v67, 3, v66
	v_add_u32_e32 v67, s96, v67
	v_and_b32_e32 v68, 7, v66
	v_lshlrev_b32_e32 v68, 4, v68
	s_and_b32 s97, s70, 3
	s_lshl_b32 s97, s97, 7
	v_add_u32_e32 v68, s97, v68
	v_lshl_add_u32 v253, v67, 9, v68
	v_add_u32_e32 v253, s9, v253
	v_sub_u32_e32 v69, 63, v67
	v_cndmask_b32_e64 v67, v69, v67, s[2:3]
	v_lshl_add_u32 v252, v67, 11, v68
	s_waitcnt vmcnt(0)
	v_mov_b32_e32 v128, 0
	v_cvt_pk_bf16_f32 v108, v5, v7
	v_cvt_pk_bf16_f32 v109, v2, v8
	v_cvt_pk_bf16_f32 v110, v3, v4
	v_cvt_pk_bf16_f32 v111, v6, v9
	s_mov_b32 s34, -1
	s_add_i32 s48, s48, 0xc800
	s_add_i32 s49, s9, s72
	s_mov_b32 s50, 38
	s_movk_i32 s51, 0x110
	s_movk_i32 s52, 0x80
	s_add_i32 s53, 0, 0x1ec00
	s_mov_b32 s54, 0xbfb8aa3b
	s_add_i32 s55, 0, 0x1f400
	s_movk_i32 s56, 0x1100
	s_add_i32 s57, 0, 0x14800
	v_mov_b32_e32 v129, v128
	v_mov_b32_e32 v130, v128
	v_mov_b32_e32 v131, v128
	v_mov_b32_e32 v132, v128
	v_mov_b32_e32 v133, v128
	v_mov_b32_e32 v134, v128
	v_mov_b32_e32 v135, v128
	v_mov_b32_e32 v0, v155
	v_mov_b32_e32 v1, v155
	v_mov_b32_e32 v2, v155
	v_mov_b32_e32 v3, v155
	v_mov_b32_e32 v4, v155
	v_mov_b32_e32 v5, v155
	v_mov_b32_e32 v6, v155
	v_mov_b32_e32 v7, v155
	v_mov_b32_e32 v8, v155
	v_mov_b32_e32 v9, v155
	v_mov_b32_e32 v10, v155
	v_mov_b32_e32 v11, v155
	v_mov_b32_e32 v12, v155
	v_mov_b32_e32 v13, v155
	v_mov_b32_e32 v14, v155
	v_mov_b32_e32 v15, v155
	v_mov_b32_e32 v16, v155
	v_mov_b32_e32 v17, v155
	v_mov_b32_e32 v18, v155
	v_mov_b32_e32 v19, v155
	v_mov_b32_e32 v20, v155
	v_mov_b32_e32 v21, v155
	v_mov_b32_e32 v22, v155
	v_mov_b32_e32 v23, v155
	v_mov_b32_e32 v24, v155
	v_mov_b32_e32 v25, v155
	v_mov_b32_e32 v26, v155
	v_mov_b32_e32 v27, v155
	v_mov_b32_e32 v28, v155
	v_mov_b32_e32 v29, v155
	v_mov_b32_e32 v30, v155
	v_mov_b32_e32 v31, v155
	v_mov_b32_e32 v32, v155
	v_mov_b32_e32 v33, v155
	v_mov_b32_e32 v34, v155
	v_mov_b32_e32 v35, v155
	v_mov_b32_e32 v36, v155
	v_mov_b32_e32 v37, v155
	v_mov_b32_e32 v38, v155
	v_mov_b32_e32 v39, v155
	v_mov_b32_e32 v40, v155
	v_mov_b32_e32 v41, v155
	v_mov_b32_e32 v42, v155
	v_mov_b32_e32 v43, v155
	v_mov_b32_e32 v44, v155
	v_mov_b32_e32 v45, v155
	v_mov_b32_e32 v46, v155
	v_mov_b32_e32 v47, v155
	v_mov_b32_e32 v48, v155
	v_mov_b32_e32 v49, v155
	v_mov_b32_e32 v50, v155
	v_mov_b32_e32 v51, v155
	v_mov_b32_e32 v52, v155
	v_mov_b32_e32 v53, v155
	v_mov_b32_e32 v54, v155
	v_mov_b32_e32 v55, v155
	v_mov_b32_e32 v56, v155
	v_mov_b32_e32 v57, v155
	v_mov_b32_e32 v58, v155
	v_mov_b32_e32 v59, v155
	v_mov_b32_e32 v60, v155
	v_mov_b32_e32 v61, v155
	v_mov_b32_e32 v62, v155
	v_mov_b32_e32 v63, v155
	v_mbcnt_lo_u32_b32 v66, -1, 0
	v_mbcnt_hi_u32_b32 v66, -1, v66
	v_bfe_u32 v67, v66, 4, 1
	v_lshlrev_b32_e32 v67, 3, v67
	v_bfe_u32 v68, v66, 2, 2
	v_add_u32_e32 v67, v67, v68
	s_and_b32 s96, s70, 3
	s_lshl_b32 s96, s96, 4
	v_add_u32_e32 v67, s96, v67
	v_lshrrev_b32_e32 v68, 5, v66
	v_lshlrev_b32_e32 v68, 6, v68
	v_and_b32_e32 v69, 3, v66
	v_lshl_add_u32 v68, v69, 4, v68
	s_lshr_b32 s96, s70, 2
	s_lshl_b32 s96, s96, 8
	v_add_u32_e32 v68, s96, v68
	v_sub_u32_e32 v69, 63, v67
	v_cndmask_b32_e64 v69, v69, v67, s[2:3]
	v_add_u32_e32 v69, s12, v69
	v_lshl_add_u32 v247, v69, 11, v68
	v_add_u32_e32 v248, 0x80, v247
	v_add_u32_e32 v67, 4, v67
	v_sub_u32_e32 v69, 63, v67
	v_cndmask_b32_e64 v69, v69, v67, s[2:3]
	v_add_u32_e32 v69, s12, v69
	v_lshl_add_u32 v249, v69, 11, v68
	v_add_u32_e32 v250, 0x80, v249
	v_mbcnt_lo_u32_b32 v64, -1, 0
	v_mbcnt_hi_u32_b32 v64, -1, v64
	s_cmp_gt_u32 s70, 0
	s_cselect_b32 s97, 1.0, 0
	v_mov_b32_e32 v238, s97
	s_cmp_gt_u32 s70, 1
	s_cselect_b32 s97, 1.0, 0
	v_mov_b32_e32 v239, s97
	s_cmp_gt_u32 s70, 2
	s_cselect_b32 s97, 1.0, 0
	v_mov_b32_e32 v240, s97
	s_cmp_gt_u32 s70, 3
	s_cselect_b32 s97, 1.0, 0
	v_mov_b32_e32 v241, s97
	s_cmp_gt_u32 s70, 4
	s_cselect_b32 s97, 1.0, 0
	v_mov_b32_e32 v242, s97
	s_cmp_gt_u32 s70, 5
	s_cselect_b32 s97, 1.0, 0
	v_mov_b32_e32 v243, s97
	s_cmp_gt_u32 s70, 6
	s_cselect_b32 s97, 1.0, 0
	v_mov_b32_e32 v244, s97
	s_mul_i32 s99, s70, 0x880
	v_and_b32_e32 v66, 2, v64
	v_lshlrev_b32_e32 v66, 1, v66
	v_and_b32_e32 v67, 4, v64
	v_lshrrev_b32_e32 v67, 1, v67
	v_and_b32_e32 v70, 0xfffffff9, v64
	v_or3_b32 v66, v66, v67, v70
	v_lshl_add_u32 v254, v66, 2, s99
	s_lshr_b32 s98, s70, 1
	s_lshl_b32 s98, s98, 12
	s_and_b32 s99, s70, 1
	s_lshl_b32 s99, s99, 8
	s_add_i32 s98, s98, s99
	v_lshrrev_b32_e32 v66, 4, v64
	v_lshlrev_b32_e32 v66, 9, v66
	v_and_b32_e32 v70, 15, v64
	v_lshl_add_u32 v66, v70, 2, v66
	v_add_u32_e32 v255, s98, v66
	s_lshr_b32 s98, s70, 2
	s_lshl_b32 s98, s98, 12
	s_and_b32 s99, s70, 3
	s_lshl_b32 s99, s99, 7
	s_add_i32 s98, s98, s99
	s_add_i32 s98, s98, 0x20000
	v_lshrrev_b32_e32 v66, 5, v64
	v_lshlrev_b32_e32 v66, 9, v66
	v_and_b32_e32 v70, 31, v64
	v_lshl_add_u32 v66, v70, 2, v66
	v_add_u32_e32 v169, s98, v66
	v_mbcnt_lo_u32_b32 v64, -1, 0
	v_mbcnt_hi_u32_b32 v64, -1, v64
	v_lshrrev_b32_e32 v66, 5, v64
	v_lshlrev_b32_e32 v66, 11, v66
	v_and_b32_e32 v67, 31, v64
	v_lshlrev_b32_e32 v70, 1, v67
	v_add3_u32 v66, s49, v66, v70
	v_and_b32_e32 v67, 1, v67
	v_mul_u32_u24_e32 v67, 0x1fe, v67
	v_add_u32_e32 v246, v66, v67
